# attention: dead v_mov and canonicalising row-max head removed from the QK->PV serial chain (on top of v15)
# speedup vs baseline: 1.0110x; 1.0099x over previous
.LBB0_680:
	v_max_f32_e32 v0, v112, v113
	v_max3_f32 v14, v114, v115, v97
	v_max3_f32 v0, v0, v96, v98
	v_max3_f32 v0, v0, v99, v116
	v_max3_f32 v14, v14, v118, v119
	v_max3_f32 v0, v0, v117, v100
	v_max3_f32 v14, v14, v102, v103
	v_max3_f32 v0, v0, v101, v120
	v_max3_f32 v14, v14, v122, v123
	v_max3_f32 v0, v0, v121, v104
	v_max3_f32 v14, v14, v106, v107
	v_max3_f32 v0, v0, v105, v124
	v_max3_f32 v14, v14, v126, v127
	v_max3_f32 v0, v0, v125, v108
	v_max3_f32 v14, v14, v110, v111
	v_max3_f32 v0, v0, v109, v14
	v_cmp_lt_f32_e32 vcc, s60, v0
	s_cbranch_vccnz .Latt_resc0
.LBB0_682:
	s_mov_b64 s[2:3], 0
.LBB0_683:
	s_waitcnt lgkmcnt(1)
	v_mfma_f32_32x32x16_bf16 v[64:79], v[16:19], v[176:179], v[64:79]
	v_exp_f32_e32 v80, v112
	v_exp_f32_e32 v81, v113
	v_exp_f32_e32 v82, v114
	v_exp_f32_e32 v83, v115
	ds_read_b128 v[112:115], v206 offset:53280
	s_waitcnt lgkmcnt(1)
	v_mfma_f32_32x32x16_bf16 v[32:47], v[202:205], v[176:179], v[32:47]
	ds_read_b128 v[14:17], v206 offset:57888
	v_exp_f32_e32 v84, v116
	v_exp_f32_e32 v85, v117
	v_exp_f32_e32 v86, v118
	v_exp_f32_e32 v87, v119
	s_waitcnt lgkmcnt(1)
	v_mfma_f32_32x32x16_bf16 v[64:79], v[112:115], v[10:13], v[64:79]
	ds_read_b128 v[116:119], v206 offset:53312
	v_exp_f32_e32 v88, v120
	v_exp_f32_e32 v89, v121
	v_exp_f32_e32 v90, v122
	v_exp_f32_e32 v91, v123
	s_waitcnt lgkmcnt(1)
	v_mfma_f32_32x32x16_bf16 v[32:47], v[14:17], v[10:13], v[32:47]
	ds_read_b128 v[112:115], v206 offset:57920
	v_exp_f32_e32 v92, v124
	v_exp_f32_e32 v93, v125
	v_exp_f32_e32 v94, v126
	v_exp_f32_e32 v95, v127
	s_waitcnt lgkmcnt(1)
	v_mfma_f32_32x32x16_bf16 v[64:79], v[116:119], v[6:9], v[64:79]
	ds_read_b128 v[10:13], v206 offset:53344
	v_exp_f32_e32 v16, v96
	v_exp_f32_e32 v17, v97
	v_exp_f32_e32 v18, v98
	v_exp_f32_e32 v19, v99
	s_waitcnt lgkmcnt(1)
	v_mfma_f32_32x32x16_bf16 v[32:47], v[112:115], v[6:9], v[32:47]
	ds_read_b128 v[96:99], v206 offset:57952
	v_exp_f32_e32 v20, v100
	v_exp_f32_e32 v21, v101
	v_exp_f32_e32 v22, v102
	v_exp_f32_e32 v23, v103
	s_waitcnt lgkmcnt(1)
	v_mfma_f32_32x32x16_bf16 v[64:79], v[10:13], v[2:5], v[64:79]
	v_exp_f32_e32 v24, v104
	v_exp_f32_e32 v25, v105
	v_exp_f32_e32 v26, v106
	v_exp_f32_e32 v27, v107
	s_waitcnt lgkmcnt(0)
	v_mfma_f32_32x32x16_bf16 v[32:47], v[96:99], v[2:5], v[32:47]
	v_exp_f32_e32 v28, v108
	v_exp_f32_e32 v29, v109
	v_exp_f32_e32 v30, v110
	v_exp_f32_e32 v31, v111
	s_and_b64 vcc, exec, s[2:3]
	s_cbranch_vccnz .Latt_oresc0

.LBB0_693:
	s_mov_b64 s[2:3], 0
.LBB0_694:
	s_waitcnt lgkmcnt(1)
	v_mfma_f32_32x32x16_bf16 v[64:79], v[16:19], v[176:179], v[64:79]
	v_exp_f32_e32 v80, v112
	v_exp_f32_e32 v81, v113
	v_exp_f32_e32 v82, v114
	v_exp_f32_e32 v83, v115
	ds_read_b128 v[112:115], v206 offset:53280
	s_waitcnt lgkmcnt(1)
	v_mfma_f32_32x32x16_bf16 v[32:47], v[202:205], v[176:179], v[32:47]
	ds_read_b128 v[14:17], v206 offset:57888
	v_exp_f32_e32 v84, v116
	v_exp_f32_e32 v85, v117
	v_exp_f32_e32 v86, v118
	v_exp_f32_e32 v87, v119
	s_waitcnt lgkmcnt(1)
	v_mfma_f32_32x32x16_bf16 v[64:79], v[112:115], v[10:13], v[64:79]
	ds_read_b128 v[116:119], v206 offset:53312
	v_exp_f32_e32 v88, v120
	v_exp_f32_e32 v89, v121
	v_exp_f32_e32 v90, v122
	v_exp_f32_e32 v91, v123
	s_waitcnt lgkmcnt(1)
	v_mfma_f32_32x32x16_bf16 v[32:47], v[14:17], v[10:13], v[32:47]
	ds_read_b128 v[112:115], v206 offset:57920
	v_exp_f32_e32 v92, v124
	v_exp_f32_e32 v93, v125
	v_exp_f32_e32 v94, v126
	v_exp_f32_e32 v95, v127
	s_waitcnt lgkmcnt(1)
	v_mfma_f32_32x32x16_bf16 v[64:79], v[116:119], v[6:9], v[64:79]
	ds_read_b128 v[10:13], v206 offset:53344
	v_exp_f32_e32 v16, v96
	v_exp_f32_e32 v17, v97
	v_exp_f32_e32 v18, v98
	v_exp_f32_e32 v19, v99
	s_waitcnt lgkmcnt(1)
	v_mfma_f32_32x32x16_bf16 v[32:47], v[112:115], v[6:9], v[32:47]
	ds_read_b128 v[96:99], v206 offset:57952
	v_exp_f32_e32 v20, v100
	v_exp_f32_e32 v21, v101
	v_exp_f32_e32 v22, v102
	v_exp_f32_e32 v23, v103
	s_waitcnt lgkmcnt(1)
	v_mfma_f32_32x32x16_bf16 v[64:79], v[10:13], v[2:5], v[64:79]
	v_exp_f32_e32 v24, v104
	v_exp_f32_e32 v25, v105
	v_exp_f32_e32 v26, v106
	v_exp_f32_e32 v27, v107
	s_waitcnt lgkmcnt(0)
	v_mfma_f32_32x32x16_bf16 v[32:47], v[96:99], v[2:5], v[32:47]
	v_exp_f32_e32 v28, v108
	v_exp_f32_e32 v29, v109
	v_exp_f32_e32 v30, v110
	v_exp_f32_e32 v31, v111
	s_and_b64 vcc, exec, s[2:3]
	s_cbranch_vccnz .Latt_oresc1
